# speedup vs baseline: 1.0143x; 1.0028x over previous
; #define MFMA(a, b, c) __builtin_amdgcn_mfma_f32_16x16x32_bf16((a), (b), (c), 0, 0, 0)
; #define ADV() { ga += 32; gb += 32; ck += 32; if (ck == K) { ck = 0; citem += gridDim.x; const int ci_ = citem < total ? citem : total - 1; SETPTR(ci_) } }
; #define WAITSTEP() { if (a2) WAITV(4); else WAITV(3); }
;     ...
;     for (int kt = 0; kt < nk; ++kt) {
;       if (VAR != 1) { const char* base = lds + scur; bf16x8 a[MI], b[4];
; #pragma unroll
;         for (int i = 0; i < 4; ++i) b[i] = *(const bf16x8*)(base + boff + i * 1024);
; #pragma unroll
;         for (int i = 0; i < MI; ++i) a[i] = *(const bf16x8*)(base + aoff + i * 1024);
; #pragma unroll
;         for (int i = 0; i < MI; ++i)
; #pragma unroll
;           for (int j = 0; j < 4; ++j) acc[i][j] = MFMA(a[i], b[j], acc[i][j]);
;         if (VAR != 2) GLDS(snext)
;     ...
;         if (MI == 8) {
;           __builtin_amdgcn_sched_group_barrier(0x100, MI + 4, 0);
; #pragma unroll
;           for (int g = 0; g < 4; ++g) { __builtin_amdgcn_sched_group_barrier(0x008, 7, 0); __builtin_amdgcn_sched_group_barrier(0x010, 1, 0); }
;           __builtin_amdgcn_sched_group_barrier(0x008, 4, 0);
;         } else if (MI == 6) {
;           __builtin_amdgcn_sched_group_barrier(0x100, MI + 4, 0);
; #pragma unroll
;           for (int g = 0; g < 4; ++g) { __builtin_amdgcn_sched_group_barrier(0x008, 5, 0); __builtin_amdgcn_sched_group_barrier(0x010, 1, 0); }
;           __builtin_amdgcn_sched_group_barrier(0x008, 4, 0);
;         }
;     ...
;       }
;       ADV()
;       if (VAR == 2) {} else WAITSTEP()
;       __builtin_amdgcn_s_barrier();
;       scur = (scur == 2 * STAGE) ? 0 : scur + STAGE;
;       snext = (snext == 2 * STAGE) ? 0 : snext + STAGE;
.Lres6_hi:
	s_add_i32 s5, s62, 0
	v_add3_u32 v107, s5, v111, v112
	v_add3_u32 v106, s5, v113, v112
	ds_read_b128 v[118:121], v107
	ds_read_b128 v[114:117], v106 offset:12288
	ds_read_b128 v[122:125], v106 offset:13312
	ds_read_b128 v[132:135], v106 offset:14336
	ds_read_b128 v[136:139], v106 offset:15360
	ds_read_b128 v[140:143], v107 offset:1024
	ds_read_b128 v[144:147], v107 offset:2048
	ds_read_b128 v[148:151], v107 offset:3072
	ds_read_b128 v[152:155], v107 offset:4096
	ds_read_b128 v[156:159], v107 offset:5120
	s_waitcnt lgkmcnt(8)
	v_mfma_f32_16x16x32_bf16 v[92:95], v[118:121], v[114:117], v[92:95]
	s_waitcnt lgkmcnt(7)
	v_mfma_f32_16x16x32_bf16 v[88:91], v[118:121], v[122:125], v[88:91]
	s_waitcnt lgkmcnt(6)
	v_mfma_f32_16x16x32_bf16 v[84:87], v[118:121], v[132:135], v[84:87]
	s_waitcnt lgkmcnt(5)
	v_mfma_f32_16x16x32_bf16 v[80:83], v[118:121], v[136:139], v[80:83]
	s_waitcnt lgkmcnt(4)
	v_mfma_f32_16x16x32_bf16 v[76:79], v[140:143], v[114:117], v[76:79]
	v_mfma_f32_16x16x32_bf16 v[72:75], v[140:143], v[122:125], v[72:75]
	v_mfma_f32_16x16x32_bf16 v[68:71], v[140:143], v[132:135], v[68:71]
	v_mfma_f32_16x16x32_bf16 v[64:67], v[140:143], v[136:139], v[64:67]
	s_waitcnt lgkmcnt(3)
	v_mfma_f32_16x16x32_bf16 v[60:63], v[144:147], v[114:117], v[60:63]
	s_add_i32 s5, s6, s100
	s_mov_b32 m0, s5
	v_lshl_add_u64 v[196:197], s[2:3], 1, v[104:105]
	v_mfma_f32_16x16x32_bf16 v[56:59], v[144:147], v[122:125], v[56:59]
	v_mfma_f32_16x16x32_bf16 v[52:55], v[144:147], v[132:135], v[52:55]
	v_mfma_f32_16x16x32_bf16 v[48:51], v[144:147], v[136:139], v[48:51]
	s_waitcnt lgkmcnt(2)
	v_mfma_f32_16x16x32_bf16 v[36:39], v[148:151], v[114:117], v[36:39]
	global_load_lds_dwordx4 v[102:103], off
	s_add_i32 m0, s5, 0x3000
	v_mfma_f32_16x16x32_bf16 v[32:35], v[148:151], v[122:125], v[32:35]
	v_mfma_f32_16x16x32_bf16 v[40:43], v[148:151], v[132:135], v[40:43]
	v_mfma_f32_16x16x32_bf16 v[44:47], v[148:151], v[136:139], v[44:47]
	s_waitcnt lgkmcnt(1)
	v_mfma_f32_16x16x32_bf16 v[16:19], v[152:155], v[114:117], v[16:19]
	v_mfma_f32_16x16x32_bf16 v[20:23], v[152:155], v[122:125], v[20:23]
	global_load_lds_dwordx4 v[104:105], off
	s_add_i32 m0, s5, 0x5000
	v_mfma_f32_16x16x32_bf16 v[24:27], v[152:155], v[132:135], v[24:27]
	v_mfma_f32_16x16x32_bf16 v[28:31], v[152:155], v[136:139], v[28:31]
	s_waitcnt lgkmcnt(0)
	v_mfma_f32_16x16x32_bf16 v[0:3], v[156:159], v[114:117], v[0:3]
	v_mfma_f32_16x16x32_bf16 v[4:7], v[156:159], v[122:125], v[4:7]
	v_mfma_f32_16x16x32_bf16 v[8:11], v[156:159], v[132:135], v[8:11]
	global_load_lds_dwordx4 v[196:197], off
	v_mfma_f32_16x16x32_bf16 v[12:15], v[156:159], v[136:139], v[12:15]
	s_add_i32 s74, s74, 32
	s_cmp_lg_u32 s74, s86
	s_waitcnt vmcnt(3)
	s_cbranch_scc0 .LBB0_1759
